# v24 with a longer (90x64 cycles) ffn_in stagger
# speedup vs baseline: 1.0008x; 1.0008x over previous
; #define TIDX tid_()
; DEVI int wave_() { return __builtin_amdgcn_readfirstlane(tid_() >> 6); }
; DEVI void phase_ffn_in(const Params& p, int l, int which, bf16_t* smem) {
;     unsigned char* ws = p.ws;
;     const bf16_t* A = (const bf16_t*)(ws + OFF_HB);
;     const bf16_t* Bt = (const bf16_t*)(ws + OFF_W + (size_t)l * SZ_LAYER + (which ? OL_W1T1 : OL_W1T0));
;     bf16_t* act = (bf16_t*)(ws + OFF_ACT);
;     const int lane = TIDX & 63, wave = wave_(), wr = wave >> 1, wc = wave & 1, l16 = lane & 15, quad = lane >> 4;
;     int tm, tn;
;     bool have = tile_map(0, 44, tm, tn);
;     if (have) gemm_issue0(A + (size_t)tm * 128 * 1024, 1024, Bt + (size_t)tn * 128 * 1024, 1024, smem);
.LBB0_778:
	s_andn2_b64 vcc, exec, s[0:1]
	s_cbranch_vccnz .LBB0_803
	s_getreg_b32 s0, hwreg(HW_REG_HW_ID, 0, 4)
	s_and_b32 s0, s0, 1
	s_cmp_eq_u32 s0, 0
	s_cbranch_scc1 .Lffn_nosleep
	s_sleep 90
